# all weight-transpose loops (prologue and the three idle-round preps): LDS reads issued eight at a time
# speedup vs baseline: 1.0098x; 1.0005x over previous
; #define LAS __attribute__((address_space(3)))
; __device__ __forceinline__ unsigned pk2(float lo, float hi) { return pg8::cvt_pk_bf16(lo, hi); }
; template <bool GATEMAP = false>
; __device__ __forceinline__ void p0_transpose_item(const float* W, int N, bf16* WT, int ldwt, int koff, const float* gain, LAS float* scr, int item, int lane) {
;     ...
;     for (int i = 0; i < 16; ++i) { LAS float* d = scr + (4 * i + ks) * 65 + n4; d[0] = v[i][0]; d[1] = v[i][1]; d[2] = v[i][2]; d[3] = v[i][3]; }
;     asm volatile("s_waitcnt lgkmcnt(0)" ::: "memory");
;     const int c = lane & 7;
; #pragma unroll
;     for (int j = 0; j < 8; ++j) { const int n = (lane >> 3) + 8 * j; const LAS float* q = scr + (8 * c) * 65 + n;
;         v4u o; o.x = pk2(q[0 * 65], q[1 * 65]); o.y = pk2(q[2 * 65], q[3 * 65]); o.z = pk2(q[4 * 65], q[5 * 65]); o.w = pk2(q[6 * 65], q[7 * 65]);
;         *(v4u*)(WT + (size_t)(nd0 + n) * ldwt + koff + k0 + 8 * c) = o; }
;     asm volatile("s_waitcnt lgkmcnt(0)" ::: "memory");
.LBB0_20:
	s_waitcnt vmcnt(15)
	ds_write2_b32 v83, v40, v41 offset1:1
	ds_write2_b32 v83, v42, v43 offset0:2 offset1:3
	v_add_u32_e32 v40, 0x410, v83
	s_waitcnt vmcnt(14)
	ds_write2_b32 v40, v16, v17 offset1:1
	v_add_u32_e32 v16, 0x418, v83
	ds_write2_b32 v16, v18, v19 offset1:1
	v_add_u32_e32 v16, 0x820, v83
	s_waitcnt vmcnt(13)
	ds_write2_b32 v16, v44, v45 offset1:1
	v_add_u32_e32 v16, 0x828, v83
	ds_write2_b32 v16, v46, v47 offset1:1
	v_add_u32_e32 v16, 0xc30, v83
	s_waitcnt vmcnt(12)
	ds_write2_b32 v16, v24, v25 offset1:1
	v_add_u32_e32 v16, 0xc38, v83
	ds_write2_b32 v16, v26, v27 offset1:1
	v_add_u32_e32 v16, 0x1040, v83
	s_waitcnt vmcnt(11)
	ds_write2_b32 v16, v36, v37 offset1:1
	v_add_u32_e32 v16, 0x1048, v83
	ds_write2_b32 v16, v38, v39 offset1:1
	v_add_u32_e32 v16, 0x1450, v83
	s_waitcnt vmcnt(10)
	ds_write2_b32 v16, v12, v13 offset1:1
	v_add_u32_e32 v12, 0x1458, v83
	ds_write2_b32 v12, v14, v15 offset1:1
	v_add_u32_e32 v12, 0x1860, v83
	s_waitcnt vmcnt(9)
	ds_write2_b32 v12, v32, v33 offset1:1
	v_add_u32_e32 v12, 0x1868, v83
	ds_write2_b32 v12, v34, v35 offset1:1
	v_add_u32_e32 v12, 0x1c70, v83
	s_waitcnt vmcnt(8)
	ds_write2_b32 v12, v8, v9 offset1:1
	v_add_u32_e32 v8, 0x1c78, v83
	ds_write2_b32 v8, v10, v11 offset1:1
	v_add_u32_e32 v8, 0x2080, v83
	s_waitcnt vmcnt(7)
	ds_write2_b32 v8, v20, v21 offset1:1
	v_add_u32_e32 v8, 0x2088, v83
	ds_write2_b32 v8, v22, v23 offset1:1
	v_add_u32_e32 v8, 0x2490, v83
	s_waitcnt vmcnt(6)
	ds_write2_b32 v8, v0, v1 offset1:1
	v_add_u32_e32 v0, 0x2498, v83
	ds_write2_b32 v0, v2, v3 offset1:1
	v_add_u32_e32 v0, 0x28a0, v83
	s_waitcnt vmcnt(5)
	ds_write2_b32 v0, v60, v61 offset1:1
	v_add_u32_e32 v0, 0x28a8, v83
	ds_write2_b32 v0, v62, v63 offset1:1
	v_add_u32_e32 v0, 0x2cb0, v83
	s_waitcnt vmcnt(4)
	ds_write2_b32 v0, v56, v57 offset1:1
	v_add_u32_e32 v0, 0x2cb8, v83
	ds_write2_b32 v0, v58, v59 offset1:1
	v_add_u32_e32 v0, 0x30c0, v83
	s_waitcnt vmcnt(3)
	ds_write2_b32 v0, v52, v53 offset1:1
	v_add_u32_e32 v0, 0x30c8, v83
	ds_write2_b32 v0, v54, v55 offset1:1
	v_add_u32_e32 v0, 0x34d0, v83
	s_waitcnt vmcnt(2)
	ds_write2_b32 v0, v48, v49 offset1:1
	v_add_u32_e32 v0, 0x34d8, v83
	ds_write2_b32 v0, v50, v51 offset1:1
	v_add_u32_e32 v0, 0x38e0, v83
	s_waitcnt vmcnt(1)
	ds_write2_b32 v0, v28, v29 offset1:1
	v_add_u32_e32 v0, 0x38e8, v83
	ds_write2_b32 v0, v30, v31 offset1:1
	v_add_u32_e32 v0, 0x3cf0, v83
	s_waitcnt vmcnt(0)
	ds_write2_b32 v0, v4, v5 offset1:1
	v_add_u32_e32 v0, 0x3cf8, v83
	ds_write2_b32 v0, v6, v7 offset1:1
	s_waitcnt lgkmcnt(0)
	v_add_u32_e32 v10, 0x400, v75
	ds_read2_b32 v[150:151], v75 offset1:65
	ds_read2_b32 v[152:153], v75 offset0:130 offset1:195
	ds_read2_b32 v[154:155], v10 offset0:4 offset1:69
	ds_read2_b32 v[156:157], v10 offset0:134 offset1:199
	ds_read2_b32 v[158:159], v75 offset0:8 offset1:73
	ds_read2_b32 v[160:161], v75 offset0:138 offset1:203
	ds_read2_b32 v[162:163], v10 offset0:12 offset1:77
	ds_read2_b32 v[164:165], v10 offset0:142 offset1:207
	s_waitcnt lgkmcnt(7)
	v_cvt_pk_bf16_f32 v0, v150, v151
	s_waitcnt lgkmcnt(6)
	v_cvt_pk_bf16_f32 v1, v152, v153
	s_waitcnt lgkmcnt(5)
	v_cvt_pk_bf16_f32 v2, v154, v155
	s_waitcnt lgkmcnt(4)
	v_cvt_pk_bf16_f32 v3, v156, v157
	v_add_u32_e32 v4, s21, v74
	s_ashr_i32 s15, s14, 31
	v_ashrrev_i32_e32 v5, 31, v4
	v_lshl_add_u64 v[6:7], s[14:15], 1, v[68:69]
	v_lshlrev_b64 v[4:5], 11, v[4:5]
	v_lshl_add_u64 v[4:5], v[6:7], 0, v[4:5]
	global_store_dwordx4 v[4:5], v[0:3], off
	s_add_i32 s20, s20, s8
	s_add_i32 s9, s9, s13
	s_waitcnt lgkmcnt(3)
	v_cvt_pk_bf16_f32 v0, v158, v159
	s_waitcnt lgkmcnt(2)
	v_cvt_pk_bf16_f32 v1, v160, v161
	s_waitcnt lgkmcnt(1)
	v_cvt_pk_bf16_f32 v2, v162, v163
	s_waitcnt lgkmcnt(0)
; #define LAS __attribute__((address_space(3)))
; __device__ __forceinline__ unsigned pk2(float lo, float hi) { return pg8::cvt_pk_bf16(lo, hi); }
; template <bool GATEMAP = false>
; __device__ __forceinline__ void p0_transpose_item(const float* W, int N, bf16* WT, int ldwt, int koff, const float* gain, LAS float* scr, int item, int lane) {
;     ...
;     const int c = lane & 7;
; #pragma unroll
;     for (int j = 0; j < 8; ++j) { const int n = (lane >> 3) + 8 * j; const LAS float* q = scr + (8 * c) * 65 + n;
;         v4u o; o.x = pk2(q[0 * 65], q[1 * 65]); o.y = pk2(q[2 * 65], q[3 * 65]); o.z = pk2(q[4 * 65], q[5 * 65]); o.w = pk2(q[6 * 65], q[7 * 65]);
;         *(v4u*)(WT + (size_t)(nd0 + n) * ldwt + koff + k0 + 8 * c) = o; }
;     asm volatile("s_waitcnt lgkmcnt(0)" ::: "memory");
	v_cvt_pk_bf16_f32 v3, v164, v165
	v_add_u32_e32 v4, s21, v76
	v_ashrrev_i32_e32 v5, 31, v4
	v_lshlrev_b64 v[4:5], 11, v[4:5]
	v_lshl_add_u64 v[4:5], v[6:7], 0, v[4:5]
	global_store_dwordx4 v[4:5], v[0:3], off
	s_add_i32 s16, s16, s17
	s_cmpk_gt_i32 s20, 0x27f
	ds_read2_b32 v[150:151], v75 offset0:16 offset1:81
	ds_read2_b32 v[152:153], v75 offset0:146 offset1:211
	ds_read2_b32 v[154:155], v10 offset0:20 offset1:85
	ds_read2_b32 v[156:157], v10 offset0:150 offset1:215
	ds_read2_b32 v[158:159], v75 offset0:24 offset1:89
	ds_read2_b32 v[160:161], v75 offset0:154 offset1:219
	ds_read2_b32 v[162:163], v10 offset0:28 offset1:93
	ds_read2_b32 v[164:165], v10 offset0:158 offset1:223
	s_waitcnt lgkmcnt(7)
	v_cvt_pk_bf16_f32 v0, v150, v151
	s_waitcnt lgkmcnt(6)
	v_cvt_pk_bf16_f32 v1, v152, v153
	s_waitcnt lgkmcnt(5)
	v_cvt_pk_bf16_f32 v2, v154, v155
	s_waitcnt lgkmcnt(4)
	v_cvt_pk_bf16_f32 v3, v156, v157
	v_add_u32_e32 v4, s21, v77
	v_ashrrev_i32_e32 v5, 31, v4
	v_lshlrev_b64 v[4:5], 11, v[4:5]
	v_lshl_add_u64 v[4:5], v[6:7], 0, v[4:5]
	global_store_dwordx4 v[4:5], v[0:3], off
	s_waitcnt lgkmcnt(3)
	s_nop 0
	v_cvt_pk_bf16_f32 v0, v158, v159
	s_waitcnt lgkmcnt(2)
	v_cvt_pk_bf16_f32 v1, v160, v161
	s_waitcnt lgkmcnt(1)
	v_cvt_pk_bf16_f32 v2, v162, v163
	s_waitcnt lgkmcnt(0)
	v_cvt_pk_bf16_f32 v3, v164, v165
	v_add_u32_e32 v4, s21, v78
	v_ashrrev_i32_e32 v5, 31, v4
	v_lshlrev_b64 v[4:5], 11, v[4:5]
	v_lshl_add_u64 v[4:5], v[6:7], 0, v[4:5]
	global_store_dwordx4 v[4:5], v[0:3], off
	ds_read2_b32 v[150:151], v75 offset0:32 offset1:97
	ds_read2_b32 v[152:153], v75 offset0:162 offset1:227
	ds_read2_b32 v[154:155], v10 offset0:36 offset1:101
	ds_read2_b32 v[156:157], v10 offset0:166 offset1:231
	ds_read2_b32 v[158:159], v75 offset0:40 offset1:105
	ds_read2_b32 v[160:161], v75 offset0:170 offset1:235
	ds_read2_b32 v[162:163], v10 offset0:44 offset1:109
	ds_read2_b32 v[164:165], v10 offset0:174 offset1:239
	s_waitcnt lgkmcnt(7)
	s_nop 0
	v_cvt_pk_bf16_f32 v0, v150, v151
	s_waitcnt lgkmcnt(6)
	v_cvt_pk_bf16_f32 v1, v152, v153
	s_waitcnt lgkmcnt(5)
	v_cvt_pk_bf16_f32 v2, v154, v155
	s_waitcnt lgkmcnt(4)
	v_cvt_pk_bf16_f32 v3, v156, v157
	v_add_u32_e32 v4, s21, v79
	v_ashrrev_i32_e32 v5, 31, v4
	v_lshlrev_b64 v[4:5], 11, v[4:5]
	v_lshl_add_u64 v[4:5], v[6:7], 0, v[4:5]
	global_store_dwordx4 v[4:5], v[0:3], off
	s_waitcnt lgkmcnt(3)
	s_nop 0
	v_cvt_pk_bf16_f32 v0, v158, v159
	s_waitcnt lgkmcnt(2)
	v_cvt_pk_bf16_f32 v1, v160, v161
	s_waitcnt lgkmcnt(1)
	v_cvt_pk_bf16_f32 v2, v162, v163
	s_waitcnt lgkmcnt(0)
	v_cvt_pk_bf16_f32 v3, v164, v165
	v_add_u32_e32 v4, s21, v80
	v_ashrrev_i32_e32 v5, 31, v4
	v_lshlrev_b64 v[4:5], 11, v[4:5]
	v_lshl_add_u64 v[4:5], v[6:7], 0, v[4:5]
	global_store_dwordx4 v[4:5], v[0:3], off
	ds_read2_b32 v[150:151], v75 offset0:48 offset1:113
	ds_read2_b32 v[152:153], v75 offset0:178 offset1:243
	ds_read2_b32 v[154:155], v10 offset0:52 offset1:117
	ds_read2_b32 v[156:157], v10 offset0:182 offset1:247
	ds_read2_b32 v[158:159], v75 offset0:56 offset1:121
	ds_read2_b32 v[160:161], v75 offset0:186 offset1:251
	ds_read2_b32 v[162:163], v10 offset0:60 offset1:125
	ds_read2_b32 v[164:165], v10 offset0:190 offset1:255
	s_waitcnt lgkmcnt(7)
	s_nop 0
	v_cvt_pk_bf16_f32 v0, v150, v151
	s_waitcnt lgkmcnt(6)
	v_cvt_pk_bf16_f32 v1, v152, v153
	s_waitcnt lgkmcnt(5)
	v_cvt_pk_bf16_f32 v2, v154, v155
	s_waitcnt lgkmcnt(4)
	v_cvt_pk_bf16_f32 v3, v156, v157
	v_add_u32_e32 v4, s21, v81
	v_ashrrev_i32_e32 v5, 31, v4
	v_lshlrev_b64 v[4:5], 11, v[4:5]
	v_lshl_add_u64 v[4:5], v[6:7], 0, v[4:5]
	global_store_dwordx4 v[4:5], v[0:3], off
	s_waitcnt lgkmcnt(3)
	s_nop 0
	v_cvt_pk_bf16_f32 v0, v158, v159
	s_waitcnt lgkmcnt(2)
	v_cvt_pk_bf16_f32 v1, v160, v161
	s_waitcnt lgkmcnt(1)
	v_cvt_pk_bf16_f32 v2, v162, v163
	s_waitcnt lgkmcnt(0)
	v_cvt_pk_bf16_f32 v3, v164, v165
	v_add_u32_e32 v4, s21, v82
	v_ashrrev_i32_e32 v5, 31, v4
	v_lshlrev_b64 v[4:5], 11, v[4:5]
	v_lshl_add_u64 v[4:5], v[6:7], 0, v[4:5]
	global_store_dwordx4 v[4:5], v[0:3], off
	s_waitcnt lgkmcnt(0)
	s_cbranch_scc1 .LBB0_25

; #define LAS __attribute__((address_space(3)))
; __host__ __device__ __forceinline__ int gate_row(int n) { if (n < 512) return n; const int base = n < 1536 ? 512 : 1536, q = n - base, h = q >> 9, t = (q & 511) >> 7, r = q & 127; return base + t * 256 + h * 128 + r; }
; template <bool GATEMAP = false>
; __device__ __forceinline__ void p0_transpose_item(const float* W, int N, bf16* WT, int ldwt, int koff, const float* gain, LAS float* scr, int item, int lane) {
;     const int nblk = N / 64, kb = item / nblk, nb = item % nblk, k0 = 64 * kb, n0 = 64 * nb; const int nd0 = GATEMAP ? gate_row(n0) : n0;
;     const int ks = lane >> 4, n4 = (lane & 15) * 4;
;     f32x4 v[16];
; #pragma unroll
;     for (int i = 0; i < 16; ++i) v[i] = *(const f32x4*)(W + (size_t)(k0 + 4 * i + ks) * N + n0 + n4);
;     if (gain) {
; #pragma unroll
;         for (int i = 0; i < 16; ++i) v[i] = v[i] * gain[k0 + 4 * i + ks];
;     }
; #pragma unroll
;     for (int i = 0; i < 16; ++i) { LAS float* d = scr + (4 * i + ks) * 65 + n4; d[0] = v[i][0]; d[1] = v[i][1]; d[2] = v[i][2]; d[3] = v[i][3]; }
; template <int PART>
; __device__ __forceinline__ void phase_prologue_late(const Params& p, LAS unsigned char* lds, int cu0) {
;     ...
;     for (int it = gw; it < I_W2; it += NGW) p0_transpose_item(p.in[23], D, (bf16*)(ws + WS_W2_0), FF, 0, nullptr, scr, it, lane);
.LBB0_508:
	s_ashr_i32 s0, s13, 31
	s_lshr_b32 s0, s0, 28
	s_add_i32 s0, s13, s0
	s_ashr_i32 s0, s0, 4
	s_lshl_b32 s2, s0, 6
	s_lshl_b32 s0, s0, 10
	v_or_b32_e32 v46, s2, v8
	s_sub_i32 s0, s4, s0
	v_or_b32_e32 v48, 4, v46
	v_or_b32_e32 v50, 8, v46
	v_or_b32_e32 v52, 12, v46
	v_or_b32_e32 v54, 16, v46
	v_or_b32_e32 v56, 20, v46
	v_or_b32_e32 v58, 24, v46
	v_or_b32_e32 v60, 28, v46
	v_or_b32_e32 v62, 32, v46
	v_or_b32_e32 v64, 36, v46
	v_or_b32_e32 v66, 40, v46
	v_or_b32_e32 v68, 44, v46
	v_or_b32_e32 v70, 48, v46
	v_or_b32_e32 v72, 52, v46
	v_or_b32_e32 v74, 56, v46
	v_or_b32_e32 v76, 60, v46
	s_ashr_i32 s1, s0, 31
	v_ashrrev_i32_e32 v47, 31, v46
	v_ashrrev_i32_e32 v49, 31, v48
	v_ashrrev_i32_e32 v51, 31, v50
	v_ashrrev_i32_e32 v53, 31, v52
	v_ashrrev_i32_e32 v55, 31, v54
	v_ashrrev_i32_e32 v57, 31, v56
	v_ashrrev_i32_e32 v59, 31, v58
	v_ashrrev_i32_e32 v61, 31, v60
	v_ashrrev_i32_e32 v63, 31, v62
	v_ashrrev_i32_e32 v65, 31, v64
	v_ashrrev_i32_e32 v67, 31, v66
	v_ashrrev_i32_e32 v69, 31, v68
	v_ashrrev_i32_e32 v71, 31, v70
	v_ashrrev_i32_e32 v73, 31, v72
	v_ashrrev_i32_e32 v75, 31, v74
	v_ashrrev_i32_e32 v77, 31, v76
	v_lshl_add_u64 v[78:79], s[0:1], 2, v[2:3]
	v_lshlrev_b64 v[46:47], 12, v[46:47]
	v_lshlrev_b64 v[80:81], 12, v[48:49]
	v_lshlrev_b64 v[50:51], 12, v[50:51]
	v_lshlrev_b64 v[52:53], 12, v[52:53]
	v_lshlrev_b64 v[54:55], 12, v[54:55]
	v_lshlrev_b64 v[56:57], 12, v[56:57]
	v_lshlrev_b64 v[58:59], 12, v[58:59]
	v_lshlrev_b64 v[60:61], 12, v[60:61]
	v_lshlrev_b64 v[62:63], 12, v[62:63]
	v_lshlrev_b64 v[64:65], 12, v[64:65]
	v_lshlrev_b64 v[66:67], 12, v[66:67]
	v_lshlrev_b64 v[68:69], 12, v[68:69]
	v_lshlrev_b64 v[70:71], 12, v[70:71]
	v_lshlrev_b64 v[72:73], 12, v[72:73]
	v_lshlrev_b64 v[74:75], 12, v[74:75]
	v_lshlrev_b64 v[76:77], 12, v[76:77]
	v_lshl_add_u64 v[46:47], v[78:79], 0, v[46:47]
	v_lshl_add_u64 v[80:81], v[78:79], 0, v[80:81]
	v_lshl_add_u64 v[82:83], v[78:79], 0, v[50:51]
	v_lshl_add_u64 v[84:85], v[78:79], 0, v[52:53]
	v_lshl_add_u64 v[86:87], v[78:79], 0, v[54:55]
	v_lshl_add_u64 v[88:89], v[78:79], 0, v[56:57]
	v_lshl_add_u64 v[90:91], v[78:79], 0, v[58:59]
	v_lshl_add_u64 v[92:93], v[78:79], 0, v[60:61]
	v_lshl_add_u64 v[94:95], v[78:79], 0, v[62:63]
	v_lshl_add_u64 v[96:97], v[78:79], 0, v[64:65]
	v_lshl_add_u64 v[98:99], v[78:79], 0, v[66:67]
	v_lshl_add_u64 v[100:101], v[78:79], 0, v[68:69]
	v_lshl_add_u64 v[102:103], v[78:79], 0, v[70:71]
	v_lshl_add_u64 v[104:105], v[78:79], 0, v[72:73]
	v_lshl_add_u64 v[106:107], v[78:79], 0, v[74:75]
	v_lshl_add_u64 v[108:109], v[78:79], 0, v[76:77]
	global_load_dwordx4 v[46:49], v[46:47], off
	s_nop 0
	global_load_dwordx4 v[50:53], v[80:81], off
	global_load_dwordx4 v[54:57], v[82:83], off
	global_load_dwordx4 v[58:61], v[84:85], off
	global_load_dwordx4 v[62:65], v[86:87], off
	global_load_dwordx4 v[66:69], v[88:89], off
	global_load_dwordx4 v[70:73], v[90:91], off
	global_load_dwordx4 v[74:77], v[92:93], off
	global_load_dwordx4 v[78:81], v[94:95], off
	global_load_dwordx4 v[82:85], v[96:97], off
	s_nop 0
	global_load_dwordx4 v[86:89], v[98:99], off
	global_load_dwordx4 v[90:93], v[100:101], off
	global_load_dwordx4 v[94:97], v[102:103], off
	s_nop 0
	global_load_dwordx4 v[98:101], v[104:105], off
	s_nop 0
	global_load_dwordx4 v[102:105], v[106:107], off
	s_nop 0
	global_load_dwordx4 v[106:109], v[108:109], off
	v_add_u32_e32 v6, s0, v9
	s_ashr_i32 s3, s2, 31
	v_ashrrev_i32_e32 v7, 31, v6
	v_lshl_add_u64 v[4:5], s[2:3], 1, v[0:1]
	v_lshlrev_b64 v[122:123], 13, v[6:7]
	v_add_u32_e32 v110, 8, v6
	v_lshl_add_u64 v[122:123], v[4:5], 0, v[122:123]
	v_ashrrev_i32_e32 v111, 31, v110
	v_lshlrev_b64 v[110:111], 13, v[110:111]
	v_add_u32_e32 v112, 16, v6
	v_lshl_add_u64 v[110:111], v[4:5], 0, v[110:111]
	v_ashrrev_i32_e32 v113, 31, v112
	v_lshlrev_b64 v[112:113], 13, v[112:113]
	v_add_u32_e32 v114, 24, v6
	v_lshl_add_u64 v[112:113], v[4:5], 0, v[112:113]
	s_waitcnt vmcnt(15)
	ds_write2_b32 v11, v46, v47 offset1:1
	ds_write2_b32 v11, v48, v49 offset0:2 offset1:3
	s_waitcnt vmcnt(14)
	ds_write2_b32 v12, v50, v51 offset1:1
	ds_write2_b32 v13, v52, v53 offset1:1
	s_waitcnt vmcnt(13)
	ds_write2_b32 v14, v54, v55 offset1:1
	ds_write2_b32 v15, v56, v57 offset1:1
	s_waitcnt vmcnt(12)
	ds_write2_b32 v16, v58, v59 offset1:1
	ds_write2_b32 v17, v60, v61 offset1:1
	s_waitcnt vmcnt(11)
	ds_write2_b32 v18, v62, v63 offset1:1
	ds_write2_b32 v19, v64, v65 offset1:1
	s_waitcnt vmcnt(10)
	ds_write2_b32 v20, v66, v67 offset1:1
	ds_write2_b32 v21, v68, v69 offset1:1
	s_waitcnt vmcnt(9)
	ds_write2_b32 v22, v70, v71 offset1:1
	ds_write2_b32 v23, v72, v73 offset1:1
	s_waitcnt vmcnt(8)
	ds_write2_b32 v24, v74, v75 offset1:1
	ds_write2_b32 v25, v76, v77 offset1:1
	s_waitcnt vmcnt(7)
	ds_write2_b32 v26, v78, v79 offset1:1
	ds_write2_b32 v27, v80, v81 offset1:1
	s_waitcnt vmcnt(6)
	ds_write2_b32 v28, v82, v83 offset1:1
	ds_write2_b32 v29, v84, v85 offset1:1
	s_waitcnt vmcnt(5)
	ds_write2_b32 v30, v86, v87 offset1:1
	ds_write2_b32 v31, v88, v89 offset1:1
	s_waitcnt vmcnt(4)
	ds_write2_b32 v32, v90, v91 offset1:1
	ds_write2_b32 v33, v92, v93 offset1:1
	s_waitcnt vmcnt(3)
	ds_write2_b32 v34, v94, v95 offset1:1
	ds_write2_b32 v35, v96, v97 offset1:1
	s_waitcnt vmcnt(2)
; #define LAS __attribute__((address_space(3)))
; __device__ __forceinline__ unsigned pk2(float lo, float hi) { return pg8::cvt_pk_bf16(lo, hi); }
; template <bool GATEMAP = false>
; __device__ __forceinline__ void p0_transpose_item(const float* W, int N, bf16* WT, int ldwt, int koff, const float* gain, LAS float* scr, int item, int lane) {
;     ...
;     for (int i = 0; i < 16; ++i) { LAS float* d = scr + (4 * i + ks) * 65 + n4; d[0] = v[i][0]; d[1] = v[i][1]; d[2] = v[i][2]; d[3] = v[i][3]; }
;     asm volatile("s_waitcnt lgkmcnt(0)" ::: "memory");
;     const int c = lane & 7;
; #pragma unroll
;     for (int j = 0; j < 8; ++j) { const int n = (lane >> 3) + 8 * j; const LAS float* q = scr + (8 * c) * 65 + n;
;         v4u o; o.x = pk2(q[0 * 65], q[1 * 65]); o.y = pk2(q[2 * 65], q[3 * 65]); o.z = pk2(q[4 * 65], q[5 * 65]); o.w = pk2(q[6 * 65], q[7 * 65]);
;         *(v4u*)(WT + (size_t)(nd0 + n) * ldwt + koff + k0 + 8 * c) = o; }
;     asm volatile("s_waitcnt lgkmcnt(0)" ::: "memory");
; template <int PART>
; __device__ __forceinline__ void phase_prologue_late(const Params& p, LAS unsigned char* lds, int cu0) {
;     ...
;     for (int it = gw; it < I_W2; it += NGW) p0_transpose_item(p.in[23], D, (bf16*)(ws + WS_W2_0), FF, 0, nullptr, scr, it, lane);
	ds_write2_b32 v36, v98, v99 offset1:1
	ds_write2_b32 v37, v100, v101 offset1:1
	s_waitcnt vmcnt(1)
	ds_write2_b32 v38, v102, v103 offset1:1
	ds_write2_b32 v39, v104, v105 offset1:1
	s_waitcnt vmcnt(0)
	ds_write2_b32 v42, v106, v107 offset1:1
	ds_write2_b32 v43, v108, v109 offset1:1
	s_waitcnt lgkmcnt(0)
	ds_read2_b32 v[198:199], v10 offset1:65
	ds_read2_b32 v[200:201], v10 offset0:130 offset1:195
	ds_read2_b32 v[202:203], v44 offset0:4 offset1:69
	ds_read2_b32 v[204:205], v44 offset0:134 offset1:199
	ds_read2_b32 v[206:207], v10 offset0:8 offset1:73
	ds_read2_b32 v[208:209], v10 offset0:138 offset1:203
	ds_read2_b32 v[210:211], v44 offset0:12 offset1:77
	ds_read2_b32 v[212:213], v44 offset0:142 offset1:207
	s_waitcnt lgkmcnt(7)
	v_cvt_pk_bf16_f32 v46, v198, v199
	s_waitcnt lgkmcnt(6)
	v_cvt_pk_bf16_f32 v47, v200, v201
	s_waitcnt lgkmcnt(5)
	v_cvt_pk_bf16_f32 v48, v202, v203
	s_waitcnt lgkmcnt(4)
	v_cvt_pk_bf16_f32 v49, v204, v205
	global_store_dwordx4 v[122:123], v[46:49], off
	v_ashrrev_i32_e32 v115, 31, v114
	v_lshlrev_b64 v[114:115], 13, v[114:115]
	s_waitcnt lgkmcnt(3)
	v_cvt_pk_bf16_f32 v46, v206, v207
	s_waitcnt lgkmcnt(2)
	v_cvt_pk_bf16_f32 v47, v208, v209
	s_waitcnt lgkmcnt(1)
	v_cvt_pk_bf16_f32 v48, v210, v211
	s_waitcnt lgkmcnt(0)
	v_cvt_pk_bf16_f32 v49, v212, v213
	global_store_dwordx4 v[110:111], v[46:49], off
	v_add_u32_e32 v116, 32, v6
	v_lshl_add_u64 v[114:115], v[4:5], 0, v[114:115]
	ds_read2_b32 v[198:199], v10 offset0:16 offset1:81
	ds_read2_b32 v[200:201], v10 offset0:146 offset1:211
	ds_read2_b32 v[202:203], v44 offset0:20 offset1:85
	ds_read2_b32 v[204:205], v44 offset0:150 offset1:215
	ds_read2_b32 v[206:207], v10 offset0:24 offset1:89
	ds_read2_b32 v[208:209], v10 offset0:154 offset1:219
	ds_read2_b32 v[210:211], v44 offset0:28 offset1:93
	ds_read2_b32 v[212:213], v44 offset0:158 offset1:223
	s_waitcnt lgkmcnt(7)
	v_cvt_pk_bf16_f32 v46, v198, v199
	s_waitcnt lgkmcnt(6)
	v_cvt_pk_bf16_f32 v47, v200, v201
	s_waitcnt lgkmcnt(5)
	v_cvt_pk_bf16_f32 v48, v202, v203
	s_waitcnt lgkmcnt(4)
	v_cvt_pk_bf16_f32 v49, v204, v205
	global_store_dwordx4 v[112:113], v[46:49], off
	v_ashrrev_i32_e32 v117, 31, v116
	v_lshlrev_b64 v[116:117], 13, v[116:117]
	s_waitcnt lgkmcnt(3)
	v_cvt_pk_bf16_f32 v46, v206, v207
	s_waitcnt lgkmcnt(2)
	v_cvt_pk_bf16_f32 v47, v208, v209
	s_waitcnt lgkmcnt(1)
	v_cvt_pk_bf16_f32 v48, v210, v211
	s_waitcnt lgkmcnt(0)
	v_cvt_pk_bf16_f32 v49, v212, v213
	global_store_dwordx4 v[114:115], v[46:49], off
	v_add_u32_e32 v118, 40, v6
	v_lshl_add_u64 v[116:117], v[4:5], 0, v[116:117]
	ds_read2_b32 v[198:199], v10 offset0:32 offset1:97
	ds_read2_b32 v[200:201], v10 offset0:162 offset1:227
	ds_read2_b32 v[202:203], v44 offset0:36 offset1:101
	ds_read2_b32 v[204:205], v44 offset0:166 offset1:231
	ds_read2_b32 v[206:207], v10 offset0:40 offset1:105
	ds_read2_b32 v[208:209], v10 offset0:170 offset1:235
	ds_read2_b32 v[210:211], v44 offset0:44 offset1:109
	ds_read2_b32 v[212:213], v44 offset0:174 offset1:239
	s_waitcnt lgkmcnt(7)
	v_cvt_pk_bf16_f32 v46, v198, v199
	s_waitcnt lgkmcnt(6)
	v_cvt_pk_bf16_f32 v47, v200, v201
	s_waitcnt lgkmcnt(5)
	v_cvt_pk_bf16_f32 v48, v202, v203
	s_waitcnt lgkmcnt(4)
	v_cvt_pk_bf16_f32 v49, v204, v205
	v_ashrrev_i32_e32 v119, 31, v118
	global_store_dwordx4 v[116:117], v[46:49], off
	v_lshlrev_b64 v[118:119], 13, v[118:119]
	v_add_u32_e32 v120, 48, v6
	s_waitcnt lgkmcnt(3)
	v_cvt_pk_bf16_f32 v46, v206, v207
	s_waitcnt lgkmcnt(2)
	v_cvt_pk_bf16_f32 v47, v208, v209
	v_lshl_add_u64 v[118:119], v[4:5], 0, v[118:119]
	s_waitcnt lgkmcnt(1)
	v_cvt_pk_bf16_f32 v48, v210, v211
	s_waitcnt lgkmcnt(0)
	v_cvt_pk_bf16_f32 v49, v212, v213
	v_ashrrev_i32_e32 v121, 31, v120
	global_store_dwordx4 v[118:119], v[46:49], off
	v_lshlrev_b64 v[120:121], 13, v[120:121]
	v_add_u32_e32 v6, 56, v6
	ds_read2_b32 v[198:199], v10 offset0:48 offset1:113
	ds_read2_b32 v[200:201], v10 offset0:178 offset1:243
	ds_read2_b32 v[202:203], v44 offset0:52 offset1:117
	ds_read2_b32 v[204:205], v44 offset0:182 offset1:247
	ds_read2_b32 v[206:207], v10 offset0:56 offset1:121
	ds_read2_b32 v[208:209], v10 offset0:186 offset1:251
	ds_read2_b32 v[210:211], v44 offset0:60 offset1:125
	ds_read2_b32 v[212:213], v44 offset0:190 offset1:255
	s_waitcnt lgkmcnt(7)
	v_cvt_pk_bf16_f32 v46, v198, v199
	s_waitcnt lgkmcnt(6)
	v_cvt_pk_bf16_f32 v47, v200, v201
	v_lshl_add_u64 v[120:121], v[4:5], 0, v[120:121]
	s_waitcnt lgkmcnt(5)
	v_cvt_pk_bf16_f32 v48, v202, v203
	s_waitcnt lgkmcnt(4)
	v_cvt_pk_bf16_f32 v49, v204, v205
	v_ashrrev_i32_e32 v7, 31, v6
	global_store_dwordx4 v[120:121], v[46:49], off
	v_lshlrev_b64 v[6:7], 13, v[6:7]
	v_lshl_add_u64 v[4:5], v[4:5], 0, v[6:7]
	s_waitcnt lgkmcnt(3)
	v_cvt_pk_bf16_f32 v46, v206, v207
	s_waitcnt lgkmcnt(2)
	v_cvt_pk_bf16_f32 v47, v208, v209
	s_waitcnt lgkmcnt(1)
	v_cvt_pk_bf16_f32 v48, v210, v211
	s_waitcnt lgkmcnt(0)
	v_cvt_pk_bf16_f32 v49, v212, v213
	global_store_dwordx4 v[4:5], v[46:49], off
	s_waitcnt lgkmcnt(0)
	s_add_i32 s13, s13, s12
	s_add_i32 s4, s4, s5
	s_cmpk_gt_i32 s13, 0x3ff
	s_cbranch_scc0 .LBB0_508
	s_cmpk_lg_i32 s7, 0xc0
	s_cbranch_scc1 .Lprep2_skipw2
	s_branch .LBB0_513

; #define LAS __attribute__((address_space(3)))
; __device__ __forceinline__ unsigned pk2(float lo, float hi) { return pg8::cvt_pk_bf16(lo, hi); }
; __host__ __device__ __forceinline__ int gate_row(int n) { if (n < 512) return n; const int base = n < 1536 ? 512 : 1536, q = n - base, h = q >> 9, t = (q & 511) >> 7, r = q & 127; return base + t * 256 + h * 128 + r; }
; template <bool GATEMAP = false>
; __device__ __forceinline__ void p0_transpose_item(const float* W, int N, bf16* WT, int ldwt, int koff, const float* gain, LAS float* scr, int item, int lane) {
;     const int nblk = N / 64, kb = item / nblk, nb = item % nblk, k0 = 64 * kb, n0 = 64 * nb; const int nd0 = GATEMAP ? gate_row(n0) : n0;
;     const int ks = lane >> 4, n4 = (lane & 15) * 4;
;     f32x4 v[16];
; #pragma unroll
;     for (int i = 0; i < 16; ++i) v[i] = *(const f32x4*)(W + (size_t)(k0 + 4 * i + ks) * N + n0 + n4);
;     if (gain) {
; #pragma unroll
;         for (int i = 0; i < 16; ++i) v[i] = v[i] * gain[k0 + 4 * i + ks];
;     }
; #pragma unroll
;     for (int i = 0; i < 16; ++i) { LAS float* d = scr + (4 * i + ks) * 65 + n4; d[0] = v[i][0]; d[1] = v[i][1]; d[2] = v[i][2]; d[3] = v[i][3]; }
;     asm volatile("s_waitcnt lgkmcnt(0)" ::: "memory");
;     const int c = lane & 7;
; #pragma unroll
;     for (int j = 0; j < 8; ++j) { const int n = (lane >> 3) + 8 * j; const LAS float* q = scr + (8 * c) * 65 + n;
;         v4u o; o.x = pk2(q[0 * 65], q[1 * 65]); o.y = pk2(q[2 * 65], q[3 * 65]); o.z = pk2(q[4 * 65], q[5 * 65]); o.w = pk2(q[6 * 65], q[7 * 65]);
;         *(v4u*)(WT + (size_t)(nd0 + n) * ldwt + koff + k0 + 8 * c) = o; }
;     asm volatile("s_waitcnt lgkmcnt(0)" ::: "memory");
; template <int PART>
; __device__ __forceinline__ void phase_prologue_late(const Params& p, LAS unsigned char* lds, int cu0) {
;     ...
;             p0_transpose_item(p.in[23] + (size_t)D * FF, D, (bf16*)(ws + WS_W2_1), FF, 0, nullptr, scr, r, lane);
.LBB0_788:
	s_cmpk_gt_i32 s6, 0x3ff
	s_mov_b64 s[4:5], -1
	s_cbranch_scc0 .LBB0_790
	s_and_b32 s5, s14, 0x3ffc0
	s_and_b32 s4, s8, 0x3c0
	v_or_b32_e32 v0, s5, v10
	s_lshl_b32 s0, s4, 2
	v_lshl_add_u64 v[52:53], v[6:7], 0, s[0:1]
	v_lshlrev_b32_e32 v0, 12, v0
	v_lshl_add_u64 v[112:113], v[52:53], 0, v[0:1]
	v_add_co_u32_e32 v56, vcc, 0x4000, v112
	s_lshl_b32 s0, s5, 1
	s_nop 0
	v_addc_co_u32_e32 v57, vcc, 0, v113, vcc
	v_add_co_u32_e32 v60, vcc, 0x8000, v112
	global_load_dwordx4 v[52:55], v[112:113], off
	s_nop 0
	global_load_dwordx4 v[56:59], v[56:57], off
	v_addc_co_u32_e32 v61, vcc, 0, v113, vcc
	v_add_co_u32_e32 v64, vcc, 0xc000, v112
	v_or_b32_e32 v0, s4, v11
	s_nop 0
	v_addc_co_u32_e32 v65, vcc, 0, v113, vcc
	v_add_co_u32_e32 v68, vcc, 0x10000, v112
	global_load_dwordx4 v[60:63], v[60:61], off
	s_nop 0
	global_load_dwordx4 v[64:67], v[64:65], off
	v_addc_co_u32_e32 v69, vcc, 0, v113, vcc
	v_add_co_u32_e32 v72, vcc, 0x14000, v112
	v_lshlrev_b32_e32 v0, 13, v0
	s_nop 0
	v_addc_co_u32_e32 v73, vcc, 0, v113, vcc
	v_add_co_u32_e32 v76, vcc, 0x18000, v112
	global_load_dwordx4 v[68:71], v[68:69], off
	s_nop 0
	global_load_dwordx4 v[72:75], v[72:73], off
	v_addc_co_u32_e32 v77, vcc, 0, v113, vcc
	v_add_co_u32_e32 v80, vcc, 0x1c000, v112
	s_nop 1
	v_addc_co_u32_e32 v81, vcc, 0, v113, vcc
	v_add_co_u32_e32 v84, vcc, 0x20000, v112
	global_load_dwordx4 v[76:79], v[76:77], off
	s_nop 0
	global_load_dwordx4 v[80:83], v[80:81], off
	v_addc_co_u32_e32 v85, vcc, 0, v113, vcc
	v_add_co_u32_e32 v88, vcc, 0x24000, v112
	s_nop 1
	v_addc_co_u32_e32 v89, vcc, 0, v113, vcc
	v_add_co_u32_e32 v92, vcc, 0x28000, v112
	global_load_dwordx4 v[84:87], v[84:85], off
	s_nop 0
	global_load_dwordx4 v[88:91], v[88:89], off
	v_addc_co_u32_e32 v93, vcc, 0, v113, vcc
	v_add_co_u32_e32 v96, vcc, 0x2c000, v112
	s_nop 1
	v_addc_co_u32_e32 v97, vcc, 0, v113, vcc
	v_add_co_u32_e32 v100, vcc, 0x30000, v112
	global_load_dwordx4 v[92:95], v[92:93], off
	s_nop 0
	global_load_dwordx4 v[96:99], v[96:97], off
	v_addc_co_u32_e32 v101, vcc, 0, v113, vcc
	v_add_co_u32_e32 v104, vcc, 0x34000, v112
	s_nop 1
	v_addc_co_u32_e32 v105, vcc, 0, v113, vcc
	global_load_dwordx4 v[100:103], v[100:101], off
	s_nop 0
	global_load_dwordx4 v[104:107], v[104:105], off
	v_add_co_u32_e32 v108, vcc, 0x38000, v112
	s_nop 1
	v_addc_co_u32_e32 v109, vcc, 0, v113, vcc
	global_load_dwordx4 v[108:111], v[108:109], off
	v_add_co_u32_e32 v112, vcc, 0x3c000, v112
	s_nop 1
	v_addc_co_u32_e32 v113, vcc, 0, v113, vcc
	global_load_dwordx4 v[112:115], v[112:113], off
	s_waitcnt vmcnt(15)
	ds_write2_b32 v20, v52, v53 offset1:1
	ds_write2_b32 v20, v54, v55 offset0:2 offset1:3
	s_waitcnt vmcnt(14)
	ds_write2_b32 v21, v56, v57 offset1:1
	ds_write2_b32 v22, v58, v59 offset1:1
	s_waitcnt vmcnt(13)
	ds_write2_b32 v23, v60, v61 offset1:1
	ds_write2_b32 v24, v62, v63 offset1:1
	s_waitcnt vmcnt(12)
	ds_write2_b32 v25, v64, v65 offset1:1
	ds_write2_b32 v26, v66, v67 offset1:1
	s_waitcnt vmcnt(11)
	ds_write2_b32 v27, v68, v69 offset1:1
	ds_write2_b32 v28, v70, v71 offset1:1
	s_waitcnt vmcnt(10)
	ds_write2_b32 v29, v72, v73 offset1:1
	ds_write2_b32 v30, v74, v75 offset1:1
	s_waitcnt vmcnt(9)
	ds_write2_b32 v31, v76, v77 offset1:1
	ds_write2_b32 v32, v78, v79 offset1:1
	s_waitcnt vmcnt(8)
	ds_write2_b32 v33, v80, v81 offset1:1
	ds_write2_b32 v34, v82, v83 offset1:1
	s_waitcnt vmcnt(7)
	ds_write2_b32 v35, v84, v85 offset1:1
	ds_write2_b32 v36, v86, v87 offset1:1
	s_waitcnt vmcnt(6)
	ds_write2_b32 v37, v88, v89 offset1:1
	ds_write2_b32 v38, v90, v91 offset1:1
	s_waitcnt vmcnt(5)
	ds_write2_b32 v39, v92, v93 offset1:1
	ds_write2_b32 v40, v94, v95 offset1:1
	s_waitcnt vmcnt(4)
	ds_write2_b32 v41, v96, v97 offset1:1
	ds_write2_b32 v42, v98, v99 offset1:1
	s_waitcnt vmcnt(3)
	ds_write2_b32 v43, v100, v101 offset1:1
	ds_write2_b32 v44, v102, v103 offset1:1
	s_waitcnt vmcnt(2)
	ds_write2_b32 v45, v104, v105 offset1:1
	ds_write2_b32 v46, v106, v107 offset1:1
	s_waitcnt vmcnt(1)
	ds_write2_b32 v47, v108, v109 offset1:1
	ds_write2_b32 v48, v110, v111 offset1:1
	s_waitcnt vmcnt(0)
	ds_write2_b32 v49, v112, v113 offset1:1
	ds_write2_b32 v50, v114, v115 offset1:1
	s_waitcnt lgkmcnt(0)
	ds_read2_b32 v[150:151], v12 offset1:65
	ds_read2_b32 v[152:153], v12 offset0:130 offset1:195
	ds_read2_b32 v[154:155], v51 offset0:4 offset1:69
	ds_read2_b32 v[156:157], v51 offset0:134 offset1:199
	ds_read2_b32 v[158:159], v12 offset0:8 offset1:73
	ds_read2_b32 v[160:161], v12 offset0:138 offset1:203
	ds_read2_b32 v[162:163], v51 offset0:12 offset1:77
	ds_read2_b32 v[164:165], v51 offset0:142 offset1:207
	s_waitcnt lgkmcnt(7)
	v_cvt_pk_bf16_f32 v52, v150, v151
	s_waitcnt lgkmcnt(6)
	v_cvt_pk_bf16_f32 v53, v152, v153
	v_lshl_add_u64 v[58:59], v[2:3], 0, s[0:1]
	s_waitcnt lgkmcnt(5)
	v_cvt_pk_bf16_f32 v54, v154, v155
	s_waitcnt lgkmcnt(4)
	v_cvt_pk_bf16_f32 v55, v156, v157
	v_lshl_add_u64 v[60:61], v[58:59], 0, v[0:1]
	global_store_dwordx4 v[60:61], v[52:55], off
	v_or_b32_e32 v0, s4, v13
	v_lshlrev_b32_e32 v0, 13, v0
	s_waitcnt lgkmcnt(3)
	v_cvt_pk_bf16_f32 v52, v158, v159
	s_waitcnt lgkmcnt(2)
	v_cvt_pk_bf16_f32 v53, v160, v161
	s_waitcnt lgkmcnt(1)
	v_cvt_pk_bf16_f32 v54, v162, v163
	s_waitcnt lgkmcnt(0)
	v_cvt_pk_bf16_f32 v55, v164, v165
	v_lshl_add_u64 v[60:61], v[58:59], 0, v[0:1]
	global_store_dwordx4 v[60:61], v[52:55], off
	v_or_b32_e32 v0, s4, v14
	v_lshlrev_b32_e32 v0, 13, v0
	ds_read2_b32 v[150:151], v12 offset0:16 offset1:81
	ds_read2_b32 v[152:153], v12 offset0:146 offset1:211
	ds_read2_b32 v[154:155], v51 offset0:20 offset1:85
	ds_read2_b32 v[156:157], v51 offset0:150 offset1:215
	ds_read2_b32 v[158:159], v12 offset0:24 offset1:89
	ds_read2_b32 v[160:161], v12 offset0:154 offset1:219
	ds_read2_b32 v[162:163], v51 offset0:28 offset1:93
	ds_read2_b32 v[164:165], v51 offset0:158 offset1:223
	s_waitcnt lgkmcnt(7)
; #define LAS __attribute__((address_space(3)))
; __device__ __forceinline__ unsigned pk2(float lo, float hi) { return pg8::cvt_pk_bf16(lo, hi); }
; __host__ __device__ __forceinline__ int gate_row(int n) { if (n < 512) return n; const int base = n < 1536 ? 512 : 1536, q = n - base, h = q >> 9, t = (q & 511) >> 7, r = q & 127; return base + t * 256 + h * 128 + r; }
; template <bool GATEMAP = false>
; __device__ __forceinline__ void p0_transpose_item(const float* W, int N, bf16* WT, int ldwt, int koff, const float* gain, LAS float* scr, int item, int lane) {
;     const int nblk = N / 64, kb = item / nblk, nb = item % nblk, k0 = 64 * kb, n0 = 64 * nb; const int nd0 = GATEMAP ? gate_row(n0) : n0;
;     const int ks = lane >> 4, n4 = (lane & 15) * 4;
;     f32x4 v[16];
; #pragma unroll
;     for (int i = 0; i < 16; ++i) v[i] = *(const f32x4*)(W + (size_t)(k0 + 4 * i + ks) * N + n0 + n4);
;     ...
;     const int c = lane & 7;
; #pragma unroll
;     for (int j = 0; j < 8; ++j) { const int n = (lane >> 3) + 8 * j; const LAS float* q = scr + (8 * c) * 65 + n;
;         v4u o; o.x = pk2(q[0 * 65], q[1 * 65]); o.y = pk2(q[2 * 65], q[3 * 65]); o.z = pk2(q[4 * 65], q[5 * 65]); o.w = pk2(q[6 * 65], q[7 * 65]);
;         *(v4u*)(WT + (size_t)(nd0 + n) * ldwt + koff + k0 + 8 * c) = o; }
;     asm volatile("s_waitcnt lgkmcnt(0)" ::: "memory");
	v_cvt_pk_bf16_f32 v52, v150, v151
	s_waitcnt lgkmcnt(6)
	v_cvt_pk_bf16_f32 v53, v152, v153
	s_waitcnt lgkmcnt(5)
	v_cvt_pk_bf16_f32 v54, v154, v155
	s_waitcnt lgkmcnt(4)
	v_cvt_pk_bf16_f32 v55, v156, v157
	v_lshl_add_u64 v[60:61], v[58:59], 0, v[0:1]
	global_store_dwordx4 v[60:61], v[52:55], off
	v_or_b32_e32 v0, s4, v15
	v_lshlrev_b32_e32 v0, 13, v0
	s_waitcnt lgkmcnt(3)
	v_cvt_pk_bf16_f32 v52, v158, v159
	s_waitcnt lgkmcnt(2)
	v_cvt_pk_bf16_f32 v53, v160, v161
	s_waitcnt lgkmcnt(1)
	v_cvt_pk_bf16_f32 v54, v162, v163
	s_waitcnt lgkmcnt(0)
	v_cvt_pk_bf16_f32 v55, v164, v165
	v_lshl_add_u64 v[60:61], v[58:59], 0, v[0:1]
	global_store_dwordx4 v[60:61], v[52:55], off
	v_or_b32_e32 v0, s4, v16
	v_lshlrev_b32_e32 v0, 13, v0
	ds_read2_b32 v[150:151], v12 offset0:32 offset1:97
	ds_read2_b32 v[152:153], v12 offset0:162 offset1:227
	ds_read2_b32 v[154:155], v51 offset0:36 offset1:101
	ds_read2_b32 v[156:157], v51 offset0:166 offset1:231
	ds_read2_b32 v[158:159], v12 offset0:40 offset1:105
	ds_read2_b32 v[160:161], v12 offset0:170 offset1:235
	ds_read2_b32 v[162:163], v51 offset0:44 offset1:109
	ds_read2_b32 v[164:165], v51 offset0:174 offset1:239
	s_waitcnt lgkmcnt(7)
	v_cvt_pk_bf16_f32 v52, v150, v151
	s_waitcnt lgkmcnt(6)
	v_cvt_pk_bf16_f32 v53, v152, v153
	s_waitcnt lgkmcnt(5)
	v_cvt_pk_bf16_f32 v54, v154, v155
	s_waitcnt lgkmcnt(4)
	v_cvt_pk_bf16_f32 v55, v156, v157
	v_lshl_add_u64 v[60:61], v[58:59], 0, v[0:1]
	global_store_dwordx4 v[60:61], v[52:55], off
	v_or_b32_e32 v0, s4, v17
	v_lshlrev_b32_e32 v0, 13, v0
	s_waitcnt lgkmcnt(3)
	v_cvt_pk_bf16_f32 v52, v158, v159
	s_waitcnt lgkmcnt(2)
	v_cvt_pk_bf16_f32 v53, v160, v161
	s_waitcnt lgkmcnt(1)
	v_cvt_pk_bf16_f32 v54, v162, v163
	s_waitcnt lgkmcnt(0)
	v_cvt_pk_bf16_f32 v55, v164, v165
	v_lshl_add_u64 v[60:61], v[58:59], 0, v[0:1]
	global_store_dwordx4 v[60:61], v[52:55], off
	v_or_b32_e32 v0, s4, v18
	v_lshlrev_b32_e32 v0, 13, v0
	ds_read2_b32 v[150:151], v12 offset0:48 offset1:113
	ds_read2_b32 v[152:153], v12 offset0:178 offset1:243
	ds_read2_b32 v[154:155], v51 offset0:52 offset1:117
	ds_read2_b32 v[156:157], v51 offset0:182 offset1:247
	ds_read2_b32 v[158:159], v12 offset0:56 offset1:121
	ds_read2_b32 v[160:161], v12 offset0:186 offset1:251
	ds_read2_b32 v[162:163], v51 offset0:60 offset1:125
	ds_read2_b32 v[164:165], v51 offset0:190 offset1:255
	s_waitcnt lgkmcnt(7)
	v_cvt_pk_bf16_f32 v52, v150, v151
	s_waitcnt lgkmcnt(6)
	v_cvt_pk_bf16_f32 v53, v152, v153
	s_waitcnt lgkmcnt(5)
	v_cvt_pk_bf16_f32 v54, v154, v155
	s_waitcnt lgkmcnt(4)
	v_cvt_pk_bf16_f32 v55, v156, v157
	v_lshl_add_u64 v[60:61], v[58:59], 0, v[0:1]
	global_store_dwordx4 v[60:61], v[52:55], off
	v_or_b32_e32 v0, s4, v19
	v_lshlrev_b32_e32 v0, 13, v0
	s_waitcnt lgkmcnt(3)
	v_cvt_pk_bf16_f32 v52, v158, v159
	s_waitcnt lgkmcnt(2)
	v_cvt_pk_bf16_f32 v53, v160, v161
	s_waitcnt lgkmcnt(1)
	v_cvt_pk_bf16_f32 v54, v162, v163
	s_waitcnt lgkmcnt(0)
	v_cvt_pk_bf16_f32 v55, v164, v165
	v_lshl_add_u64 v[56:57], v[58:59], 0, v[0:1]
	global_store_dwordx4 v[56:57], v[52:55], off
	s_waitcnt lgkmcnt(0)
	s_mov_b64 s[4:5], 0
.LBB0_790:
	s_andn2_b64 vcc, exec, s[4:5]
	s_cbranch_vccnz .LBB0_787
	s_ashr_i32 s0, s6, 31
	s_lshr_b32 s0, s0, 26
	s_add_i32 s0, s6, s0
	s_and_b32 s24, s0, 0xffffffc0
	s_lshl_b32 s0, s0, 6
	s_and_b32 s0, s0, 0xfffff000
	v_or_b32_e32 v116, s24, v10
	s_sub_i32 s4, s8, s0
	v_or_b32_e32 v118, 4, v116
	v_or_b32_e32 v120, 8, v116
	v_or_b32_e32 v122, 12, v116
	v_or_b32_e32 v124, 16, v116
	v_or_b32_e32 v126, 20, v116
	v_or_b32_e32 v128, 24, v116
	v_or_b32_e32 v130, 28, v116
	v_or_b32_e32 v132, 32, v116
	v_or_b32_e32 v134, 36, v116
	v_or_b32_e32 v136, 40, v116
	v_or_b32_e32 v138, 44, v116
	v_or_b32_e32 v140, 48, v116
	v_or_b32_e32 v142, 52, v116
	v_or_b32_e32 v144, 56, v116
	v_or_b32_e32 v146, 60, v116
	s_ashr_i32 s5, s4, 31
	v_ashrrev_i32_e32 v117, 31, v116
	v_ashrrev_i32_e32 v119, 31, v118
	v_ashrrev_i32_e32 v121, 31, v120
	v_ashrrev_i32_e32 v123, 31, v122
	v_ashrrev_i32_e32 v125, 31, v124
	v_ashrrev_i32_e32 v127, 31, v126
	v_ashrrev_i32_e32 v129, 31, v128
	v_ashrrev_i32_e32 v131, 31, v130
	v_ashrrev_i32_e32 v133, 31, v132
	v_ashrrev_i32_e32 v135, 31, v134
	v_ashrrev_i32_e32 v137, 31, v136
	v_ashrrev_i32_e32 v139, 31, v138
	v_ashrrev_i32_e32 v141, 31, v140
	v_ashrrev_i32_e32 v143, 31, v142
	v_ashrrev_i32_e32 v145, 31, v144
	v_ashrrev_i32_e32 v147, 31, v146
	v_lshl_add_u64 v[108:109], s[4:5], 2, v[8:9]
	v_lshlrev_b64 v[52:53], 14, v[116:117]
	v_lshlrev_b64 v[54:55], 14, v[118:119]
	v_lshlrev_b64 v[60:61], 14, v[120:121]
	v_lshlrev_b64 v[62:63], 14, v[122:123]
	v_lshlrev_b64 v[68:69], 14, v[124:125]
	v_lshlrev_b64 v[70:71], 14, v[126:127]
	v_lshlrev_b64 v[76:77], 14, v[128:129]
	v_lshlrev_b64 v[78:79], 14, v[130:131]
	v_lshlrev_b64 v[84:85], 14, v[132:133]
	v_lshlrev_b64 v[86:87], 14, v[134:135]
	v_lshlrev_b64 v[92:93], 14, v[136:137]
	v_lshlrev_b64 v[94:95], 14, v[138:139]
	v_lshlrev_b64 v[100:101], 14, v[140:141]
	v_lshlrev_b64 v[102:103], 14, v[142:143]
	v_lshlrev_b64 v[110:111], 14, v[144:145]
	v_lshlrev_b64 v[112:113], 14, v[146:147]
	v_lshl_add_u64 v[52:53], v[108:109], 0, v[52:53]
	v_lshl_add_u64 v[56:57], v[108:109], 0, v[54:55]
	v_lshl_add_u64 v[60:61], v[108:109], 0, v[60:61]
	v_lshl_add_u64 v[64:65], v[108:109], 0, v[62:63]
	v_lshl_add_u64 v[68:69], v[108:109], 0, v[68:69]
	v_lshl_add_u64 v[72:73], v[108:109], 0, v[70:71]
	v_lshl_add_u64 v[76:77], v[108:109], 0, v[76:77]
	v_lshl_add_u64 v[80:81], v[108:109], 0, v[78:79]
	v_lshl_add_u64 v[84:85], v[108:109], 0, v[84:85]
	v_lshl_add_u64 v[88:89], v[108:109], 0, v[86:87]
	v_lshl_add_u64 v[92:93], v[108:109], 0, v[92:93]
	v_lshl_add_u64 v[96:97], v[108:109], 0, v[94:95]
; #define LAS __attribute__((address_space(3)))
; template <bool GATEMAP = false>
; __device__ __forceinline__ void p0_transpose_item(const float* W, int N, bf16* WT, int ldwt, int koff, const float* gain, LAS float* scr, int item, int lane) {
;     ...
;     for (int i = 0; i < 16; ++i) v[i] = *(const f32x4*)(W + (size_t)(k0 + 4 * i + ks) * N + n0 + n4);
;     if (gain) {
; #pragma unroll
;         for (int i = 0; i < 16; ++i) v[i] = v[i] * gain[k0 + 4 * i + ks];
;     }
; #pragma unroll
;     for (int i = 0; i < 16; ++i) { LAS float* d = scr + (4 * i + ks) * 65 + n4; d[0] = v[i][0]; d[1] = v[i][1]; d[2] = v[i][2]; d[3] = v[i][3]; }
	v_lshl_add_u64 v[100:101], v[108:109], 0, v[100:101]
	v_lshl_add_u64 v[104:105], v[108:109], 0, v[102:103]
	v_lshl_add_u64 v[110:111], v[108:109], 0, v[110:111]
	v_lshl_add_u64 v[112:113], v[108:109], 0, v[112:113]
	v_lshl_add_u64 v[116:117], v[116:117], 2, s[2:3]
	global_load_dwordx4 v[52:55], v[52:53], off
	s_nop 0
	global_load_dwordx4 v[56:59], v[56:57], off
	s_nop 0
	global_load_dwordx4 v[60:63], v[60:61], off
	s_nop 0
	global_load_dwordx4 v[64:67], v[64:65], off
	s_nop 0
	global_load_dwordx4 v[68:71], v[68:69], off
	s_nop 0
	global_load_dwordx4 v[72:75], v[72:73], off
	s_nop 0
	global_load_dwordx4 v[76:79], v[76:77], off
	s_nop 0
	global_load_dwordx4 v[80:83], v[80:81], off
	s_nop 0
	global_load_dwordx4 v[84:87], v[84:85], off
	s_nop 0
	global_load_dwordx4 v[88:91], v[88:89], off
	s_nop 0
	global_load_dwordx4 v[92:95], v[92:93], off
	s_nop 0
	global_load_dwordx4 v[96:99], v[96:97], off
	s_nop 0
	global_load_dwordx4 v[100:103], v[100:101], off
	s_nop 0
	global_load_dwordx4 v[104:107], v[104:105], off
	s_nop 0
	global_load_dwordx4 v[108:111], v[110:111], off
	s_nop 0
	global_load_dwordx4 v[112:115], v[112:113], off
	s_ashr_i32 s25, s24, 31
	global_load_dword v0, v[116:117], off
	v_lshl_add_u64 v[116:117], v[118:119], 2, s[2:3]
	v_lshl_add_u64 v[118:119], v[120:121], 2, s[2:3]
	v_lshl_add_u64 v[120:121], v[122:123], 2, s[2:3]
	v_lshl_add_u64 v[122:123], v[124:125], 2, s[2:3]
	v_lshl_add_u64 v[124:125], v[126:127], 2, s[2:3]
	v_lshl_add_u64 v[126:127], v[128:129], 2, s[2:3]
	v_lshl_add_u64 v[128:129], v[130:131], 2, s[2:3]
	v_lshl_add_u64 v[130:131], v[132:133], 2, s[2:3]
	v_lshl_add_u64 v[132:133], v[134:135], 2, s[2:3]
	v_lshl_add_u64 v[134:135], v[136:137], 2, s[2:3]
	v_lshl_add_u64 v[136:137], v[138:139], 2, s[2:3]
	v_lshl_add_u64 v[138:139], v[140:141], 2, s[2:3]
	v_lshl_add_u64 v[140:141], v[142:143], 2, s[2:3]
	v_lshl_add_u64 v[142:143], v[144:145], 2, s[2:3]
	v_lshl_add_u64 v[144:145], v[146:147], 2, s[2:3]
	global_load_dword v116, v[116:117], off
	s_waitcnt vmcnt(1)
	v_pk_mul_f32 v[52:53], v[52:53], v[0:1] op_sel_hi:[1,0]
	global_load_dword v118, v[118:119], off
	v_pk_mul_f32 v[54:55], v[54:55], v[0:1] op_sel_hi:[1,0]
	global_load_dword v120, v[120:121], off
	s_nop 0
	global_load_dword v122, v[122:123], off
	s_nop 0
	global_load_dword v124, v[124:125], off
	s_nop 0
	global_load_dword v126, v[126:127], off
	s_nop 0
	global_load_dword v128, v[128:129], off
	s_nop 0
	global_load_dword v130, v[130:131], off
	s_waitcnt vmcnt(7)
	v_pk_mul_f32 v[58:59], v[58:59], v[116:117] op_sel_hi:[1,0]
	global_load_dword v132, v[132:133], off
	v_pk_mul_f32 v[56:57], v[56:57], v[116:117] op_sel_hi:[1,0]
	global_load_dword v134, v[134:135], off
	s_waitcnt vmcnt(8)
	v_pk_mul_f32 v[62:63], v[62:63], v[118:119] op_sel_hi:[1,0]
	global_load_dword v136, v[136:137], off
	v_pk_mul_f32 v[60:61], v[60:61], v[118:119] op_sel_hi:[1,0]
	global_load_dword v138, v[138:139], off
	s_waitcnt vmcnt(9)
	v_pk_mul_f32 v[66:67], v[66:67], v[120:121] op_sel_hi:[1,0]
	global_load_dword v140, v[140:141], off
	v_pk_mul_f32 v[64:65], v[64:65], v[120:121] op_sel_hi:[1,0]
	global_load_dword v142, v[142:143], off
	s_waitcnt vmcnt(10)
	v_pk_mul_f32 v[70:71], v[70:71], v[122:123] op_sel_hi:[1,0]
	global_load_dword v144, v[144:145], off
	v_pk_mul_f32 v[68:69], v[68:69], v[122:123] op_sel_hi:[1,0]
	s_waitcnt vmcnt(10)
	v_pk_mul_f32 v[74:75], v[74:75], v[124:125] op_sel_hi:[1,0]
	v_pk_mul_f32 v[72:73], v[72:73], v[124:125] op_sel_hi:[1,0]
	s_waitcnt vmcnt(9)
	v_pk_mul_f32 v[78:79], v[78:79], v[126:127] op_sel_hi:[1,0]
	v_pk_mul_f32 v[76:77], v[76:77], v[126:127] op_sel_hi:[1,0]
	s_waitcnt vmcnt(8)
	v_pk_mul_f32 v[82:83], v[82:83], v[128:129] op_sel_hi:[1,0]
	v_pk_mul_f32 v[80:81], v[80:81], v[128:129] op_sel_hi:[1,0]
	s_waitcnt vmcnt(7)
	v_pk_mul_f32 v[86:87], v[86:87], v[130:131] op_sel_hi:[1,0]
	v_pk_mul_f32 v[84:85], v[84:85], v[130:131] op_sel_hi:[1,0]
	s_waitcnt vmcnt(6)
	v_pk_mul_f32 v[90:91], v[90:91], v[132:133] op_sel_hi:[1,0]
	v_pk_mul_f32 v[88:89], v[88:89], v[132:133] op_sel_hi:[1,0]
	s_waitcnt vmcnt(5)
	v_pk_mul_f32 v[94:95], v[94:95], v[134:135] op_sel_hi:[1,0]
	v_pk_mul_f32 v[92:93], v[92:93], v[134:135] op_sel_hi:[1,0]
	s_waitcnt vmcnt(4)
	v_pk_mul_f32 v[98:99], v[98:99], v[136:137] op_sel_hi:[1,0]
	v_pk_mul_f32 v[96:97], v[96:97], v[136:137] op_sel_hi:[1,0]
	s_waitcnt vmcnt(3)
	v_pk_mul_f32 v[102:103], v[102:103], v[138:139] op_sel_hi:[1,0]
	v_pk_mul_f32 v[100:101], v[100:101], v[138:139] op_sel_hi:[1,0]
	s_waitcnt vmcnt(2)
	v_pk_mul_f32 v[106:107], v[106:107], v[140:141] op_sel_hi:[1,0]
	v_pk_mul_f32 v[104:105], v[104:105], v[140:141] op_sel_hi:[1,0]
	s_waitcnt vmcnt(1)
	v_pk_mul_f32 v[110:111], v[110:111], v[142:143] op_sel_hi:[1,0]
	v_pk_mul_f32 v[108:109], v[108:109], v[142:143] op_sel_hi:[1,0]
	s_waitcnt vmcnt(0)
	v_pk_mul_f32 v[114:115], v[114:115], v[144:145] op_sel_hi:[1,0]
	v_pk_mul_f32 v[112:113], v[112:113], v[144:145] op_sel_hi:[1,0]
	ds_write2_b32 v20, v52, v53 offset1:1
	ds_write2_b32 v20, v54, v55 offset0:2 offset1:3
	ds_write2_b32 v21, v56, v57 offset1:1
	ds_write2_b32 v22, v58, v59 offset1:1
	ds_write2_b32 v23, v60, v61 offset1:1
	ds_write2_b32 v24, v62, v63 offset1:1
	ds_write2_b32 v25, v64, v65 offset1:1
	ds_write2_b32 v26, v66, v67 offset1:1
	ds_write2_b32 v27, v68, v69 offset1:1
	ds_write2_b32 v28, v70, v71 offset1:1
	ds_write2_b32 v29, v72, v73 offset1:1
	ds_write2_b32 v30, v74, v75 offset1:1
	ds_write2_b32 v31, v76, v77 offset1:1
	ds_write2_b32 v32, v78, v79 offset1:1
	ds_write2_b32 v33, v80, v81 offset1:1
	ds_write2_b32 v34, v82, v83 offset1:1
	ds_write2_b32 v35, v84, v85 offset1:1
	ds_write2_b32 v36, v86, v87 offset1:1
	ds_write2_b32 v37, v88, v89 offset1:1
	ds_write2_b32 v38, v90, v91 offset1:1
	ds_write2_b32 v39, v92, v93 offset1:1
	ds_write2_b32 v40, v94, v95 offset1:1
	ds_write2_b32 v41, v96, v97 offset1:1
	ds_write2_b32 v42, v98, v99 offset1:1
	ds_write2_b32 v43, v100, v101 offset1:1
	ds_write2_b32 v44, v102, v103 offset1:1
	ds_write2_b32 v45, v104, v105 offset1:1
	ds_write2_b32 v46, v106, v107 offset1:1
	ds_write2_b32 v47, v108, v109 offset1:1
	ds_write2_b32 v48, v110, v111 offset1:1
	ds_write2_b32 v49, v112, v113 offset1:1
	ds_write2_b32 v50, v114, v115 offset1:1
	s_waitcnt lgkmcnt(0)
; #define LAS __attribute__((address_space(3)))
; __device__ __forceinline__ unsigned pk2(float lo, float hi) { return pg8::cvt_pk_bf16(lo, hi); }
; template <bool GATEMAP = false>
; __device__ __forceinline__ void p0_transpose_item(const float* W, int N, bf16* WT, int ldwt, int koff, const float* gain, LAS float* scr, int item, int lane) {
;     ...
;     const int c = lane & 7;
; #pragma unroll
;     for (int j = 0; j < 8; ++j) { const int n = (lane >> 3) + 8 * j; const LAS float* q = scr + (8 * c) * 65 + n;
;         v4u o; o.x = pk2(q[0 * 65], q[1 * 65]); o.y = pk2(q[2 * 65], q[3 * 65]); o.z = pk2(q[4 * 65], q[5 * 65]); o.w = pk2(q[6 * 65], q[7 * 65]);
;         *(v4u*)(WT + (size_t)(nd0 + n) * ldwt + koff + k0 + 8 * c) = o; }
;     asm volatile("s_waitcnt lgkmcnt(0)" ::: "memory");
	ds_read2_b32 v[150:151], v12 offset1:65
	ds_read2_b32 v[152:153], v12 offset0:130 offset1:195
	ds_read2_b32 v[154:155], v51 offset0:4 offset1:69
	ds_read2_b32 v[156:157], v51 offset0:134 offset1:199
	ds_read2_b32 v[158:159], v12 offset0:8 offset1:73
	ds_read2_b32 v[160:161], v12 offset0:138 offset1:203
	ds_read2_b32 v[162:163], v51 offset0:12 offset1:77
	ds_read2_b32 v[164:165], v51 offset0:142 offset1:207
	s_waitcnt lgkmcnt(7)
	v_cvt_pk_bf16_f32 v52, v150, v151
	s_waitcnt lgkmcnt(6)
	v_cvt_pk_bf16_f32 v53, v152, v153
	s_waitcnt lgkmcnt(5)
	v_cvt_pk_bf16_f32 v54, v154, v155
	s_waitcnt lgkmcnt(4)
	v_cvt_pk_bf16_f32 v55, v156, v157
	v_add_u32_e32 v56, s4, v11
	v_ashrrev_i32_e32 v57, 31, v56
	v_lshl_add_u64 v[58:59], s[24:25], 1, v[4:5]
	v_lshlrev_b64 v[62:63], 11, v[56:57]
	v_lshl_add_u64 v[62:63], v[58:59], 0, v[62:63]
	global_store_dwordx4 v[62:63], v[52:55], off
	s_waitcnt lgkmcnt(3)
	s_nop 0
	v_cvt_pk_bf16_f32 v52, v158, v159
	s_waitcnt lgkmcnt(2)
	v_cvt_pk_bf16_f32 v53, v160, v161
	s_waitcnt lgkmcnt(1)
	v_cvt_pk_bf16_f32 v54, v162, v163
	s_waitcnt lgkmcnt(0)
	v_cvt_pk_bf16_f32 v55, v164, v165
	v_add_u32_e32 v60, 8, v56
	v_ashrrev_i32_e32 v61, 31, v60
	v_lshlrev_b64 v[60:61], 11, v[60:61]
	v_lshl_add_u64 v[60:61], v[58:59], 0, v[60:61]
	global_store_dwordx4 v[60:61], v[52:55], off
	ds_read2_b32 v[150:151], v12 offset0:16 offset1:81
	ds_read2_b32 v[152:153], v12 offset0:146 offset1:211
	ds_read2_b32 v[154:155], v51 offset0:20 offset1:85
	ds_read2_b32 v[156:157], v51 offset0:150 offset1:215
	ds_read2_b32 v[158:159], v12 offset0:24 offset1:89
	ds_read2_b32 v[160:161], v12 offset0:154 offset1:219
	ds_read2_b32 v[162:163], v51 offset0:28 offset1:93
	ds_read2_b32 v[164:165], v51 offset0:158 offset1:223
	s_waitcnt lgkmcnt(7)
	s_nop 0
	v_cvt_pk_bf16_f32 v52, v150, v151
	s_waitcnt lgkmcnt(6)
	v_cvt_pk_bf16_f32 v53, v152, v153
	s_waitcnt lgkmcnt(5)
	v_cvt_pk_bf16_f32 v54, v154, v155
	s_waitcnt lgkmcnt(4)
	v_cvt_pk_bf16_f32 v55, v156, v157
	v_add_u32_e32 v60, 16, v56
	v_ashrrev_i32_e32 v61, 31, v60
	v_lshlrev_b64 v[60:61], 11, v[60:61]
	v_lshl_add_u64 v[60:61], v[58:59], 0, v[60:61]
	global_store_dwordx4 v[60:61], v[52:55], off
	s_waitcnt lgkmcnt(3)
	s_nop 0
	v_cvt_pk_bf16_f32 v52, v158, v159
	s_waitcnt lgkmcnt(2)
	v_cvt_pk_bf16_f32 v53, v160, v161
	s_waitcnt lgkmcnt(1)
	v_cvt_pk_bf16_f32 v54, v162, v163
	s_waitcnt lgkmcnt(0)
	v_cvt_pk_bf16_f32 v55, v164, v165
	v_add_u32_e32 v60, 24, v56
	v_ashrrev_i32_e32 v61, 31, v60
	v_lshlrev_b64 v[60:61], 11, v[60:61]
	v_lshl_add_u64 v[60:61], v[58:59], 0, v[60:61]
	global_store_dwordx4 v[60:61], v[52:55], off
	ds_read2_b32 v[150:151], v12 offset0:32 offset1:97
	ds_read2_b32 v[152:153], v12 offset0:162 offset1:227
	ds_read2_b32 v[154:155], v51 offset0:36 offset1:101
	ds_read2_b32 v[156:157], v51 offset0:166 offset1:231
	ds_read2_b32 v[158:159], v12 offset0:40 offset1:105
	ds_read2_b32 v[160:161], v12 offset0:170 offset1:235
	ds_read2_b32 v[162:163], v51 offset0:44 offset1:109
	ds_read2_b32 v[164:165], v51 offset0:174 offset1:239
	s_waitcnt lgkmcnt(7)
	s_nop 0
	v_cvt_pk_bf16_f32 v52, v150, v151
	s_waitcnt lgkmcnt(6)
	v_cvt_pk_bf16_f32 v53, v152, v153
	s_waitcnt lgkmcnt(5)
	v_cvt_pk_bf16_f32 v54, v154, v155
	s_waitcnt lgkmcnt(4)
	v_cvt_pk_bf16_f32 v55, v156, v157
	v_add_u32_e32 v60, 32, v56
	v_ashrrev_i32_e32 v61, 31, v60
	v_lshlrev_b64 v[60:61], 11, v[60:61]
	v_lshl_add_u64 v[60:61], v[58:59], 0, v[60:61]
	global_store_dwordx4 v[60:61], v[52:55], off
	s_waitcnt lgkmcnt(3)
	s_nop 0
	v_cvt_pk_bf16_f32 v52, v158, v159
	s_waitcnt lgkmcnt(2)
	v_cvt_pk_bf16_f32 v53, v160, v161
	s_waitcnt lgkmcnt(1)
	v_cvt_pk_bf16_f32 v54, v162, v163
	s_waitcnt lgkmcnt(0)
	v_cvt_pk_bf16_f32 v55, v164, v165
	v_add_u32_e32 v60, 40, v56
	v_ashrrev_i32_e32 v61, 31, v60
	v_lshlrev_b64 v[60:61], 11, v[60:61]
	v_lshl_add_u64 v[60:61], v[58:59], 0, v[60:61]
	global_store_dwordx4 v[60:61], v[52:55], off
	ds_read2_b32 v[150:151], v12 offset0:48 offset1:113
	ds_read2_b32 v[152:153], v12 offset0:178 offset1:243
	ds_read2_b32 v[154:155], v51 offset0:52 offset1:117
	ds_read2_b32 v[156:157], v51 offset0:182 offset1:247
	ds_read2_b32 v[158:159], v12 offset0:56 offset1:121
	ds_read2_b32 v[160:161], v12 offset0:186 offset1:251
	ds_read2_b32 v[162:163], v51 offset0:60 offset1:125
	ds_read2_b32 v[164:165], v51 offset0:190 offset1:255
	s_waitcnt lgkmcnt(7)
	s_nop 0
	v_cvt_pk_bf16_f32 v52, v150, v151
	s_waitcnt lgkmcnt(6)
	v_cvt_pk_bf16_f32 v53, v152, v153
	s_waitcnt lgkmcnt(5)
	v_cvt_pk_bf16_f32 v54, v154, v155
	s_waitcnt lgkmcnt(4)
	v_cvt_pk_bf16_f32 v55, v156, v157
	v_add_u32_e32 v60, 48, v56
	v_ashrrev_i32_e32 v61, 31, v60
	v_lshlrev_b64 v[60:61], 11, v[60:61]
	v_add_u32_e32 v56, 56, v56
	v_lshl_add_u64 v[60:61], v[58:59], 0, v[60:61]
	v_ashrrev_i32_e32 v57, 31, v56
	global_store_dwordx4 v[60:61], v[52:55], off
	v_lshlrev_b64 v[56:57], 11, v[56:57]
	v_lshl_add_u64 v[56:57], v[58:59], 0, v[56:57]
	s_waitcnt lgkmcnt(3)
	v_cvt_pk_bf16_f32 v52, v158, v159
	s_waitcnt lgkmcnt(2)
	v_cvt_pk_bf16_f32 v53, v160, v161
	s_waitcnt lgkmcnt(1)
	v_cvt_pk_bf16_f32 v54, v162, v163
	s_waitcnt lgkmcnt(0)
	v_cvt_pk_bf16_f32 v55, v164, v165
	global_store_dwordx4 v[56:57], v[52:55], off
	s_waitcnt lgkmcnt(0)
	s_branch .LBB0_787
